# static priority raise (s_setprio 1) for waves 4-7 over the whole mixer phase, per-MFMA-group priority flips in the attention tile bodies deleted (timing-only)
# speedup vs baseline: 1.0019x; 1.0019x over previous
.LBB0_111:
	s_add_u32 s22, s8, 0x13100000
	s_addc_u32 s23, s9, 0
	v_writelane_b32 v255, s30, 15
	s_cmp_eq_u32 s100, 1
	s_cbranch_scc0 .Lmx_conv
	s_mov_b32 s100, 2
	s_setprio 1
	s_waitcnt vmcnt(0)
	s_branch .LBB0_114

.LBB0_156:
	s_waitcnt vmcnt(15)
	ds_write_b128 v154, v[84:87] offset:4096
	s_waitcnt vmcnt(13)
	ds_write_b128 v154, v[88:91] offset:5120
	s_waitcnt vmcnt(11)
	ds_write_b128 v154, v[96:99] offset:6144
	s_waitcnt vmcnt(9)
	ds_write_b128 v154, v[104:107] offset:7168
	ds_read_b128 v[48:51], v156 offset:4096
	ds_read_b128 v[164:167], v157 offset:4096
	ds_read_b128 v[168:171], v158 offset:4096
	ds_read_b128 v[172:175], v159 offset:4096
	ds_write_b128 v155, v[80:83]
	ds_write_b128 v155, v[92:95] offset:1024
	ds_write_b128 v155, v[100:103] offset:2048
	s_waitcnt vmcnt(8)
	ds_write_b128 v155, v[108:111] offset:3072
	s_waitcnt lgkmcnt(7)
	v_mfma_f32_32x32x16_bf16 v[48:63], v[48:51], v[64:67], 0
	s_waitcnt lgkmcnt(6)
	v_mfma_f32_32x32x16_bf16 v[48:63], v[164:167], v[68:71], v[48:63]
	s_waitcnt lgkmcnt(5)
	v_mfma_f32_32x32x16_bf16 v[48:63], v[168:171], v[72:75], v[48:63]
	s_waitcnt lgkmcnt(4)
	v_mfma_f32_32x32x16_bf16 v[48:63], v[172:175], v[76:79], v[48:63]
	v_mul_lo_u32 v14, s38, v151
	v_add3_u32 v14, s59, v144, v14
	v_cvt_f32_i32_e32 v167, v14
	v_cvt_f32_ubyte0_e32 v169, s38
	s_mov_b64 s[38:39], -1
	s_and_b64 vcc, exec, s[36:37]
	s_cbranch_vccz .LBB0_158
	v_mov_b32_e32 v14, v167
	s_mov_b64 s[38:39], 0
	s_cmp_gt_i32 s59, 0
	s_cbranch_scc1 .Lattn_slow_a
	s_cmp_gt_u32 s74, 10
	s_cbranch_scc1 .Lattn_fastA_a
	s_cmp_gt_u32 s74, 8
	s_cbranch_scc1 .Lattn_fastB_a

.LBB0_162:
	v_sub_f32_e32 v14, v14, v162
	v_sub_f32_e32 v15, v15, v162
	v_exp_f32_e32 v14, v14
	v_sub_f32_e32 v164, v164, v162
	v_sub_f32_e32 v165, v165, v162
	v_exp_f32_e32 v15, v15
	v_sub_f32_e32 v163, v163, v162
	v_add_f32_e32 v167, 0, v14
	v_exp_f32_e32 v169, v164
	v_add_f32_e32 v164, v167, v15
	v_exp_f32_e32 v167, v165
	v_sub_f32_e32 v165, v166, v162
	s_waitcnt lgkmcnt(0)
	s_nop 0
	v_exp_f32_e32 v166, v165
	v_sub_f32_e32 v165, v168, v162
	v_exp_f32_e32 v163, v163
	v_exp_f32_e32 v168, v165
	v_sub_f32_e32 v165, v170, v162
	s_nop 0
	v_exp_f32_e32 v170, v165
	v_sub_f32_e32 v165, v171, v162
	v_add_f32_e32 v164, v164, v163
	v_exp_f32_e32 v171, v165
	v_sub_f32_e32 v165, v172, v162
	v_add_f32_e32 v164, v164, v169
	v_exp_f32_e32 v172, v165
	v_sub_f32_e32 v165, v173, v162
	v_add_f32_e32 v164, v164, v167
	v_add_f32_e32 v164, v164, v166
	v_exp_f32_e32 v173, v165
	v_sub_f32_e32 v165, v174, v162
	v_add_f32_e32 v164, v164, v168
	v_cvt_pk_bf16_f32 v166, v167, v166
	v_add_f32_e32 v164, v164, v170
	v_exp_f32_e32 v174, v165
	v_sub_f32_e32 v165, v175, v162
	v_add_f32_e32 v164, v164, v171
	v_add_f32_e32 v164, v164, v172
	v_exp_f32_e32 v175, v165
	v_sub_f32_e32 v165, v176, v162
	v_add_f32_e32 v164, v164, v173
	v_cvt_pk_bf16_f32 v167, v168, v170
	v_exp_f32_e32 v176, v165
	v_add_f32_e32 v164, v164, v174
	v_sub_f32_e32 v165, v177, v162
	v_add_f32_e32 v164, v164, v175
	v_cvt_pk_bf16_f32 v168, v171, v172
	v_exp_f32_e32 v177, v165
	v_sub_f32_e32 v165, v178, v162
	v_add_f32_e32 v164, v164, v176
	v_cvt_pk_bf16_f32 v170, v175, v176
	v_exp_f32_e32 v178, v165
	v_add_f32_e32 v164, v164, v177
	v_cvt_pk_bf16_f32 v165, v163, v169
	v_add_f32_e32 v164, v164, v178
	v_add_f32_e32 v143, v143, v164
	v_cvt_pk_bf16_f32 v164, v14, v15
	v_cvt_pk_bf16_f32 v169, v173, v174
	v_cvt_pk_bf16_f32 v171, v177, v178
	v_mfma_f32_32x32x16_bf16 v[16:31], v[60:63], v[164:167], v[16:31]
	v_mfma_f32_32x32x16_bf16 v[32:47], v[52:55], v[164:167], v[32:47]
	v_mfma_f32_32x32x16_bf16 v[16:31], v[56:59], v[168:171], v[16:31]
	v_mfma_f32_32x32x16_bf16 v[32:47], v[48:51], v[168:171], v[32:47]
	s_cmp_gt_i32 s71, 22
	s_cbranch_scc1 .LBB0_134
	s_lshl_b32 s72, s71, 5
	s_add_i32 s74, s71, 1
	s_cmp_gt_i32 s71, 21
	s_cbranch_scc1 .Lnt_slow_a
	s_lshl_b32 s4, s74, 7
	s_sub_i32 s5, s67, s4
	s_add_i32 s6, s68, s4
	s_cmp_gt_u32 s74, 10
	s_cselect_b32 s5, s5, s6
	s_add_i32 s5, s5, 0x7c
	s_add_i32 s6, s70, s72
	s_add_i32 s6, s6, 31
	s_cmp_lt_u32 s74, 8
	s_cselect_b32 s5, s6, s5
	s_cmp_gt_i32 s5, -1
	s_cbranch_scc1 .LBB0_173

.LBB0_184:
	s_waitcnt vmcnt(15)
	ds_write_b128 v154, v[2:5] offset:4096
	s_waitcnt vmcnt(13)
	ds_write_b128 v154, v[112:115] offset:5120
	s_waitcnt vmcnt(11)
	ds_write_b128 v154, v[120:123] offset:6144
	s_waitcnt vmcnt(9)
	ds_write_b128 v154, v[128:131] offset:7168
	ds_read_b128 v[48:51], v156 offset:4096
	ds_read_b128 v[164:167], v157 offset:4096
	ds_read_b128 v[168:171], v158 offset:4096
	ds_read_b128 v[172:175], v159 offset:4096
	ds_write_b128 v155, v[6:9]
	ds_write_b128 v155, v[10:13] offset:1024
	ds_write_b128 v155, v[116:119] offset:2048
	s_waitcnt vmcnt(8)
	ds_write_b128 v155, v[124:127] offset:3072
	s_waitcnt lgkmcnt(7)
	v_mfma_f32_32x32x16_bf16 v[48:63], v[48:51], v[64:67], 0
	s_waitcnt lgkmcnt(6)
	v_mfma_f32_32x32x16_bf16 v[48:63], v[164:167], v[68:71], v[48:63]
	s_waitcnt lgkmcnt(5)
	v_mfma_f32_32x32x16_bf16 v[48:63], v[168:171], v[72:75], v[48:63]
	s_waitcnt lgkmcnt(4)
	v_mfma_f32_32x32x16_bf16 v[48:63], v[172:175], v[76:79], v[48:63]
	v_mul_lo_u32 v0, s52, v151
	v_add3_u32 v0, s73, v144, v0
	v_cvt_f32_i32_e32 v166, v0
	v_cvt_f32_ubyte0_e32 v168, s52
	s_mov_b64 s[52:53], -1
	s_and_b64 vcc, exec, s[38:39]
	s_cbranch_vccz .LBB0_186
	v_mov_b32_e32 v0, v166
	s_mov_b64 s[52:53], 0
	s_cmp_gt_i32 s73, 0
	s_cbranch_scc1 .Lattn_slow_b
	s_cmp_gt_u32 s71, 10
	s_cbranch_scc1 .Lattn_fastA_b
	s_cmp_gt_u32 s71, 8
	s_cbranch_scc1 .Lattn_fastB_b

.LBB0_190:
	v_sub_f32_e32 v164, v164, v162
	v_sub_f32_e32 v0, v0, v162
	v_exp_f32_e32 v168, v164
	v_sub_f32_e32 v164, v165, v162
	v_sub_f32_e32 v165, v167, v162
	v_sub_f32_e32 v14, v14, v162
	v_exp_f32_e32 v167, v165
	v_sub_f32_e32 v165, v169, v162
	v_exp_f32_e32 v0, v0
	v_sub_f32_e32 v15, v15, v162
	v_exp_f32_e32 v169, v165
	v_sub_f32_e32 v165, v170, v162
	v_exp_f32_e32 v14, v14
	v_sub_f32_e32 v163, v163, v162
	v_add_f32_e32 v166, 0, v0
	v_exp_f32_e32 v15, v15
	v_add_f32_e32 v166, v166, v14
	v_exp_f32_e32 v170, v165
	v_sub_f32_e32 v165, v171, v162
	v_exp_f32_e32 v163, v163
	s_nop 0
	v_add_f32_e32 v166, v166, v15
	v_exp_f32_e32 v178, v164
	v_add_f32_e32 v164, v166, v163
	v_exp_f32_e32 v171, v165
	v_sub_f32_e32 v165, v172, v162
	v_add_f32_e32 v164, v164, v168
	s_waitcnt lgkmcnt(0)
	s_nop 0
	v_exp_f32_e32 v172, v165
	v_add_f32_e32 v164, v164, v178
	v_sub_f32_e32 v165, v173, v162
	v_add_f32_e32 v164, v164, v167
	v_add_f32_e32 v164, v164, v169
	v_exp_f32_e32 v173, v165
	v_sub_f32_e32 v165, v174, v162
	v_add_f32_e32 v164, v164, v170
	v_add_f32_e32 v164, v164, v171
	v_exp_f32_e32 v174, v165
	v_sub_f32_e32 v165, v175, v162
	v_cvt_pk_bf16_f32 v166, v168, v178
	v_add_f32_e32 v164, v164, v172
	v_exp_f32_e32 v175, v165
	v_add_f32_e32 v164, v164, v173
	v_sub_f32_e32 v165, v176, v162
	v_add_f32_e32 v164, v164, v174
	v_cvt_pk_bf16_f32 v167, v167, v169
	v_exp_f32_e32 v176, v165
	v_sub_f32_e32 v165, v177, v162
	v_add_f32_e32 v164, v164, v175
	v_cvt_pk_bf16_f32 v168, v170, v171
	v_exp_f32_e32 v177, v165
	v_add_f32_e32 v164, v164, v176
	v_cvt_pk_bf16_f32 v165, v15, v163
	v_add_f32_e32 v164, v164, v177
	v_add_f32_e32 v143, v143, v164
	v_cvt_pk_bf16_f32 v164, v0, v14
	v_cvt_pk_bf16_f32 v169, v172, v173
	v_cvt_pk_bf16_f32 v170, v174, v175
	v_cvt_pk_bf16_f32 v171, v176, v177
	v_mfma_f32_32x32x16_bf16 v[16:31], v[60:63], v[164:167], v[16:31]
	v_mfma_f32_32x32x16_bf16 v[32:47], v[52:55], v[164:167], v[32:47]
	v_mfma_f32_32x32x16_bf16 v[16:31], v[56:59], v[168:171], v[16:31]
	v_mfma_f32_32x32x16_bf16 v[32:47], v[48:51], v[168:171], v[32:47]
	s_and_b64 s[26:27], s[36:37], s[26:27]
	s_and_b64 s[4:5], exec, s[36:37]
	s_cselect_b32 s74, s74, s71
	s_xor_b64 s[36:37], s[36:37], -1
	s_andn2_b64 vcc, exec, s[36:37]
	s_cbranch_vccnz .LBB0_135
	s_branch .LBB0_205

.Lmx_end:
	s_setprio 0
